# GEMM unit scheduler: skip the rcp-based batch division when the linear unit index is below the per-batch tile count (4 loop instances)
# baseline (speedup 1.0000x reference)
.LBB0_511:
	s_cmp_lt_u32 s46, s6
	s_cbranch_scc0 .Lq_slow_0
	s_mov_b32 s2, 0
	s_branch .LBB0_512

.LBB0_566:
	s_cmp_lt_u32 s50, s26
	s_cbranch_scc0 .Lq_slow_1
	s_mov_b32 s46, 0
	s_branch .LBB0_567

.LBB0_1068:
	s_cmp_lt_u32 s36, s6
	s_cbranch_scc0 .Lq_slow_2
	s_mov_b32 s4, 0
	s_branch .LBB0_1069

.LBB0_1121:
	s_cmp_lt_u32 s46, s0
	s_cbranch_scc0 .Lq_slow_3
	s_mov_b32 s36, 0
	s_branch .LBB0_1122
